# q-up and k-up GEMM epilogues: the 8 per-row-group row-scale loads issued together instead of 8 serialized load-wait round trips
# baseline (speedup 1.0000x reference)
; DI unsigned pk2(float lo, float hi) { const f32x2 v = {lo, hi}; const hwbf16x2 b = __builtin_convertvector(v, hwbf16x2); return __builtin_bit_cast(unsigned, b); }
; DI float frsq(float x) { return __builtin_amdgcn_rsqf(x); }
;     DI void operator()(const f32x4 (&acc)[2][2][4][2], const Unit& u, int wr, int wc, int fr, int fq) const {
;     ...
;                 const int row = row0 + ai * HALF + m * 16;
;                 float rs = 1.f, rowacc = 0.f;
;                 if (mode == EPI_STORE || mode == EPI_Q) { if (rscale) rs = rscale[row]; }
;                 if (mode == EPI_SWIGLU) rs = frsq(rowsq[row] * (1.0f / DM) + 1e-6f);
; #pragma unroll
;                 for (int bj = 0; bj < 2; ++bj) {
;                     const int col = col0 + bj * HALF;
;                     f32x4 v0 = acc[ai][bj][m][0], v1 = acc[ai][bj][m][1];
;                     if (mode == EPI_STORE) {
;                         if (col < ncols) { v0 = v0 * rs; v1 = v1 * rs; u32x4 w; w.x = pk2(v0[0], v0[1]); w.y = pk2(v0[2], v0[3]); w.z = pk2(v1[0], v1[1]); w.w = pk2(v1[2], v1[3]);
;                             *(u32x4*)(O + (size_t)row * ldc + col) = w; }
;                     } else if (mode == EPI_Q) {
;                         const float sc = rs * qscale; v0 = v0 * sc; v1 = v1 * sc;
;                         const int c192 = col % 192;
;                         if (c192 >= 128) {
;                             const int i0 = (c192 - 128) >> 1, pos = row & (S_ - 1);
;                             const f32x4 cs = *(const f32x4*)(cosT + pos * 32 + i0), sn = *(const f32x4*)(sinT + pos * 32 + i0);
;                             float a, b;
;                             a = v0[0]; b = v0[1]; v0[0] = a * cs[0] - b * sn[0]; v0[1] = a * sn[0] + b * cs[0];
;                             a = v0[2]; b = v0[3]; v0[2] = a * cs[1] - b * sn[1]; v0[3] = a * sn[1] + b * cs[1];
;                             a = v1[0]; b = v1[1]; v1[0] = a * cs[2] - b * sn[2]; v1[1] = a * sn[2] + b * cs[2];
;                             a = v1[2]; b = v1[3]; v1[2] = a * cs[3] - b * sn[3]; v1[3] = a * sn[3] + b * cs[3];
;                         }
;                         u32x4 w; w.x = pk2(v0[0], v0[1]); w.y = pk2(v0[2], v0[3]); w.z = pk2(v1[0], v1[1]); w.w = pk2(v1[2], v1[3]);
;                         *(u32x4*)(O + (size_t)row * ldc + col) = w;
.LBB0_346:
	v_lshl_add_u32 v150, s67, 8, v156
	v_ashrrev_i32_e32 v151, 31, v150
	v_lshl_add_u64 v[152:153], v[150:151], 2, s[18:19]
	global_load_dword v236, v[152:153], off
	global_load_dword v237, v[152:153], off offset:64
	global_load_dword v238, v[152:153], off offset:128
	global_load_dword v239, v[152:153], off offset:192
	global_load_dword v240, v[152:153], off offset:512
	global_load_dword v241, v[152:153], off offset:576
	global_load_dword v242, v[152:153], off offset:640
	global_load_dword v243, v[152:153], off offset:704
	v_lshl_or_b32 v146, s30, 8, v158
	v_mul_hi_i32 v148, v146, s55
	v_lshrrev_b32_e32 v149, 31, v148
	v_lshrrev_b32_e32 v148, 5, v148
	v_add_u32_e32 v148, v148, v149
	v_mul_lo_u32 v148, v148, s42
	v_lshlrev_b32_e32 v147, 5, v150
	v_sub_u32_e32 v148, v146, v148
	v_and_b32_e32 v147, 0x3f9e0, v147
	v_cmp_lt_i32_e32 vcc, s58, v148
	v_add_u32_e32 v148, 0xffffff80, v148
	v_lshrrev_b32_e32 v148, 1, v148
	s_waitcnt vmcnt(0)
	v_mov_b32_e32 v136, v236
	v_mul_f32_e32 v154, 0x3dd53b94, v136
	v_pk_mul_f32 v[126:127], v[126:127], v[154:155] op_sel_hi:[1,0]
	v_pk_mul_f32 v[124:125], v[124:125], v[154:155] op_sel_hi:[1,0]
	v_pk_mul_f32 v[122:123], v[122:123], v[154:155] op_sel_hi:[1,0]
	v_pk_mul_f32 v[120:121], v[120:121], v[154:155] op_sel_hi:[1,0]
	v_lshlrev_b32_e32 v136, 2, v147
	s_and_saveexec_b64 s[4:5], vcc
	s_cbranch_execz .LBB0_348
	v_mov_b32_e32 v149, v137
	v_lshl_add_u64 v[162:163], s[10:11], 0, v[136:137]
	v_lshlrev_b64 v[164:165], 2, v[148:149]
	v_lshl_add_u64 v[170:171], v[162:163], 0, v[164:165]
	v_lshl_add_u64 v[162:163], s[14:15], 0, v[136:137]
	v_lshl_add_u64 v[162:163], v[162:163], 0, v[164:165]
	global_load_dwordx4 v[162:165], v[162:163], off
	s_nop 0
	global_load_dwordx4 v[170:173], v[170:171], off
	s_waitcnt vmcnt(1)
	v_pk_mul_f32 v[174:175], v[124:125], v[162:163] op_sel:[1,0] op_sel_hi:[0,0]
	v_pk_mul_f32 v[178:179], v[120:121], v[164:165] op_sel:[1,0] op_sel_hi:[0,0]
	s_waitcnt vmcnt(0)
	v_pk_mul_f32 v[176:177], v[124:125], v[170:171]
	v_mov_b32_e32 v162, v171
	v_mul_f32_e32 v166, v127, v163
	v_mul_f32_e32 v168, v127, v171
	v_pk_mul_f32 v[180:181], v[120:121], v[172:173]
	v_mov_b32_e32 v164, v173
	v_mul_f32_e32 v182, v123, v165
	v_mul_f32_e32 v184, v123, v173
	v_pk_fma_f32 v[124:125], v[124:125], v[170:171], v[174:175] op_sel_hi:[1,0,1]
	v_mov_b32_e32 v170, v163
	v_pk_fma_f32 v[120:121], v[120:121], v[172:173], v[178:179] op_sel_hi:[1,0,1]
	v_mov_b32_e32 v172, v165
	v_pk_fma_f32 v[186:187], v[126:127], v[162:163], v[166:167] op_sel_hi:[1,1,0] neg_lo:[0,0,1] neg_hi:[0,0,1]
	v_pk_fma_f32 v[162:163], v[122:123], v[164:165], v[182:183] op_sel_hi:[1,1,0] neg_lo:[0,0,1] neg_hi:[0,0,1]
	v_pk_fma_f32 v[164:165], v[126:127], v[170:171], v[168:169] op_sel_hi:[1,1,0]
	v_pk_fma_f32 v[170:171], v[122:123], v[172:173], v[184:185] op_sel_hi:[1,1,0]
	v_sub_f32_e32 v120, v180, v178
	v_sub_f32_e32 v124, v176, v174
	v_mov_b32_e32 v122, v162
	v_mov_b32_e32 v126, v186
	v_mov_b32_e32 v123, v170
	v_mov_b32_e32 v127, v164

; DI unsigned pk2(float lo, float hi) { const f32x2 v = {lo, hi}; const hwbf16x2 b = __builtin_convertvector(v, hwbf16x2); return __builtin_bit_cast(unsigned, b); }
; DI float frsq(float x) { return __builtin_amdgcn_rsqf(x); }
;     DI void operator()(const f32x4 (&acc)[2][2][4][2], const Unit& u, int wr, int wc, int fr, int fq) const {
;     ...
;                 const int row = row0 + ai * HALF + m * 16;
;                 float rs = 1.f, rowacc = 0.f;
;                 if (mode == EPI_STORE || mode == EPI_Q) { if (rscale) rs = rscale[row]; }
;                 if (mode == EPI_SWIGLU) rs = frsq(rowsq[row] * (1.0f / DM) + 1e-6f);
; #pragma unroll
;                 for (int bj = 0; bj < 2; ++bj) {
;                     const int col = col0 + bj * HALF;
;                     f32x4 v0 = acc[ai][bj][m][0], v1 = acc[ai][bj][m][1];
;                     if (mode == EPI_STORE) {
;                         if (col < ncols) { v0 = v0 * rs; v1 = v1 * rs; u32x4 w; w.x = pk2(v0[0], v0[1]); w.y = pk2(v0[2], v0[3]); w.z = pk2(v1[0], v1[1]); w.w = pk2(v1[2], v1[3]);
;                             *(u32x4*)(O + (size_t)row * ldc + col) = w; }
;                     } else if (mode == EPI_Q) {
;                         const float sc = rs * qscale; v0 = v0 * sc; v1 = v1 * sc;
;                         const int c192 = col % 192;
;                         if (c192 >= 128) {
;                             const int i0 = (c192 - 128) >> 1, pos = row & (S_ - 1);
;                             const f32x4 cs = *(const f32x4*)(cosT + pos * 32 + i0), sn = *(const f32x4*)(sinT + pos * 32 + i0);
;                             float a, b;
;                             a = v0[0]; b = v0[1]; v0[0] = a * cs[0] - b * sn[0]; v0[1] = a * sn[0] + b * cs[0];
;                             a = v0[2]; b = v0[3]; v0[2] = a * cs[1] - b * sn[1]; v0[3] = a * sn[1] + b * cs[1];
;                             a = v1[0]; b = v1[1]; v1[0] = a * cs[2] - b * sn[2]; v1[1] = a * sn[2] + b * cs[2];
;                             a = v1[2]; b = v1[3]; v1[2] = a * cs[3] - b * sn[3]; v1[3] = a * sn[3] + b * cs[3];
;                         }
;                         u32x4 w; w.x = pk2(v0[0], v0[1]); w.y = pk2(v0[2], v0[3]); w.z = pk2(v1[0], v1[1]); w.w = pk2(v1[2], v1[3]);
;                         *(u32x4*)(O + (size_t)row * ldc + col) = w;
.LBB0_350:
	s_or_b64 exec, exec, s[30:31]
	v_cvt_pk_bf16_f32 v124, v116, v117
	v_or_b32_e32 v116, 16, v150
	v_cvt_pk_bf16_f32 v125, v122, v123
	v_cvt_pk_bf16_f32 v126, v114, v115
	v_cvt_pk_bf16_f32 v127, v118, v119
	v_ashrrev_i32_e32 v117, 31, v116
	global_store_dwordx4 v[120:121], v[124:127], off offset:256
	v_lshl_add_u64 v[114:115], v[116:117], 2, s[18:19]
	v_mov_b32_e32 v113, v237
	v_lshlrev_b32_e32 v114, 5, v116
	v_and_b32_e32 v115, 0x3fbe0, v114
	v_lshlrev_b32_e32 v136, 2, v115
	v_mul_f32_e32 v114, 0x3dd53b94, v113
	v_pk_mul_f32 v[110:111], v[110:111], v[114:115] op_sel_hi:[1,0]
	v_pk_mul_f32 v[108:109], v[108:109], v[114:115] op_sel_hi:[1,0]
	v_pk_mul_f32 v[106:107], v[106:107], v[114:115] op_sel_hi:[1,0]
	v_pk_mul_f32 v[104:105], v[104:105], v[114:115] op_sel_hi:[1,0]
	s_and_saveexec_b64 s[30:31], vcc
	s_cbranch_execz .LBB0_352
	v_mov_b32_e32 v149, v137
	v_lshl_add_u64 v[118:119], s[10:11], 0, v[136:137]
	v_lshlrev_b64 v[120:121], 2, v[148:149]
	v_lshl_add_u64 v[122:123], v[118:119], 0, v[120:121]
	v_lshl_add_u64 v[118:119], s[14:15], 0, v[136:137]
	v_lshl_add_u64 v[118:119], v[118:119], 0, v[120:121]
	global_load_dwordx4 v[118:121], v[118:119], off
	s_nop 0
	global_load_dwordx4 v[122:125], v[122:123], off
	s_waitcnt vmcnt(1)
	v_pk_mul_f32 v[126:127], v[108:109], v[118:119] op_sel:[1,0] op_sel_hi:[0,0]
	v_pk_mul_f32 v[170:171], v[104:105], v[120:121] op_sel:[1,0] op_sel_hi:[0,0]
	s_waitcnt vmcnt(0)
	v_pk_mul_f32 v[154:155], v[108:109], v[122:123]
	v_mov_b32_e32 v118, v123
	v_mul_f32_e32 v162, v111, v119
	v_mul_f32_e32 v164, v111, v123
	v_pk_mul_f32 v[172:173], v[104:105], v[124:125]
	v_mov_b32_e32 v120, v125
	v_mul_f32_e32 v166, v107, v121
	v_mul_f32_e32 v168, v107, v125
	v_pk_fma_f32 v[108:109], v[108:109], v[122:123], v[126:127] op_sel_hi:[1,0,1]
	v_mov_b32_e32 v122, v119
	v_pk_fma_f32 v[104:105], v[104:105], v[124:125], v[170:171] op_sel_hi:[1,0,1]
	v_mov_b32_e32 v124, v121
	v_pk_fma_f32 v[162:163], v[110:111], v[118:119], v[162:163] op_sel_hi:[1,1,0] neg_lo:[0,0,1] neg_hi:[0,0,1]
	v_pk_fma_f32 v[118:119], v[106:107], v[120:121], v[166:167] op_sel_hi:[1,1,0] neg_lo:[0,0,1] neg_hi:[0,0,1]
	v_pk_fma_f32 v[120:121], v[110:111], v[122:123], v[164:165] op_sel_hi:[1,1,0]
	v_pk_fma_f32 v[122:123], v[106:107], v[124:125], v[168:169] op_sel_hi:[1,1,0]
	v_sub_f32_e32 v104, v172, v170
	v_sub_f32_e32 v108, v154, v126
	v_mov_b32_e32 v106, v118
	v_mov_b32_e32 v110, v162
	v_mov_b32_e32 v107, v122
	v_mov_b32_e32 v111, v120

; DI unsigned pk2(float lo, float hi) { const f32x2 v = {lo, hi}; const hwbf16x2 b = __builtin_convertvector(v, hwbf16x2); return __builtin_bit_cast(unsigned, b); }
; DI float frsq(float x) { return __builtin_amdgcn_rsqf(x); }
;     DI void operator()(const f32x4 (&acc)[2][2][4][2], const Unit& u, int wr, int wc, int fr, int fq) const {
;     ...
;                 const int row = row0 + ai * HALF + m * 16;
;                 float rs = 1.f, rowacc = 0.f;
;                 if (mode == EPI_STORE || mode == EPI_Q) { if (rscale) rs = rscale[row]; }
;                 if (mode == EPI_SWIGLU) rs = frsq(rowsq[row] * (1.0f / DM) + 1e-6f);
; #pragma unroll
;                 for (int bj = 0; bj < 2; ++bj) {
;                     const int col = col0 + bj * HALF;
;                     f32x4 v0 = acc[ai][bj][m][0], v1 = acc[ai][bj][m][1];
;                     if (mode == EPI_STORE) {
;                         if (col < ncols) { v0 = v0 * rs; v1 = v1 * rs; u32x4 w; w.x = pk2(v0[0], v0[1]); w.y = pk2(v0[2], v0[3]); w.z = pk2(v1[0], v1[1]); w.w = pk2(v1[2], v1[3]);
;                             *(u32x4*)(O + (size_t)row * ldc + col) = w; }
;                     } else if (mode == EPI_Q) {
;                         const float sc = rs * qscale; v0 = v0 * sc; v1 = v1 * sc;
;                         const int c192 = col % 192;
;                         if (c192 >= 128) {
;                             const int i0 = (c192 - 128) >> 1, pos = row & (S_ - 1);
;                             const f32x4 cs = *(const f32x4*)(cosT + pos * 32 + i0), sn = *(const f32x4*)(sinT + pos * 32 + i0);
;                             float a, b;
;                             a = v0[0]; b = v0[1]; v0[0] = a * cs[0] - b * sn[0]; v0[1] = a * sn[0] + b * cs[0];
;                             a = v0[2]; b = v0[3]; v0[2] = a * cs[1] - b * sn[1]; v0[3] = a * sn[1] + b * cs[1];
;                             a = v1[0]; b = v1[1]; v1[0] = a * cs[2] - b * sn[2]; v1[1] = a * sn[2] + b * cs[2];
;                             a = v1[2]; b = v1[3]; v1[2] = a * cs[3] - b * sn[3]; v1[3] = a * sn[3] + b * cs[3];
;                         }
;                         u32x4 w; w.x = pk2(v0[0], v0[1]); w.y = pk2(v0[2], v0[3]); w.z = pk2(v1[0], v1[1]); w.w = pk2(v1[2], v1[3]);
;                         *(u32x4*)(O + (size_t)row * ldc + col) = w;
.LBB0_354:
	s_or_b64 exec, exec, s[30:31]
	v_cvt_pk_bf16_f32 v100, v100, v101
	v_cvt_pk_bf16_f32 v101, v102, v103
	v_cvt_pk_bf16_f32 v103, v98, v99
	v_or_b32_e32 v98, 32, v150
	v_cvt_pk_bf16_f32 v102, v96, v97
	v_ashrrev_i32_e32 v99, 31, v98
	global_store_dwordx4 v[104:105], v[100:103], off offset:256
	v_lshl_add_u64 v[96:97], v[98:99], 2, s[18:19]
	v_mov_b32_e32 v96, v238
	v_lshlrev_b32_e32 v97, 5, v98
	v_and_b32_e32 v97, 0x3fde0, v97
	v_lshlrev_b32_e32 v136, 2, v97
	v_mul_f32_e32 v96, 0x3dd53b94, v96
	v_pk_mul_f32 v[94:95], v[94:95], v[96:97] op_sel_hi:[1,0]
	v_pk_mul_f32 v[92:93], v[92:93], v[96:97] op_sel_hi:[1,0]
	v_pk_mul_f32 v[90:91], v[90:91], v[96:97] op_sel_hi:[1,0]
	v_pk_mul_f32 v[88:89], v[88:89], v[96:97] op_sel_hi:[1,0]
	s_and_saveexec_b64 s[30:31], vcc
	s_cbranch_execz .LBB0_356
	v_mov_b32_e32 v149, v137
	v_lshl_add_u64 v[100:101], s[10:11], 0, v[136:137]
	v_lshlrev_b64 v[102:103], 2, v[148:149]
	v_lshl_add_u64 v[104:105], v[100:101], 0, v[102:103]
	v_lshl_add_u64 v[100:101], s[14:15], 0, v[136:137]
	v_lshl_add_u64 v[100:101], v[100:101], 0, v[102:103]
	global_load_dwordx4 v[100:103], v[100:101], off
	s_nop 0
	global_load_dwordx4 v[104:107], v[104:105], off
	s_waitcnt vmcnt(1)
	v_pk_mul_f32 v[108:109], v[92:93], v[100:101] op_sel:[1,0] op_sel_hi:[0,0]
	v_pk_mul_f32 v[118:119], v[88:89], v[102:103] op_sel:[1,0] op_sel_hi:[0,0]
	s_waitcnt vmcnt(0)
	v_pk_mul_f32 v[110:111], v[92:93], v[104:105]
	v_mov_b32_e32 v100, v105
	v_mul_f32_e32 v114, v95, v101
	v_mul_f32_e32 v116, v95, v105
	v_pk_mul_f32 v[120:121], v[88:89], v[106:107]
	v_mov_b32_e32 v102, v107
	v_mul_f32_e32 v122, v91, v103
	v_mul_f32_e32 v124, v91, v107
	v_pk_fma_f32 v[92:93], v[92:93], v[104:105], v[108:109] op_sel_hi:[1,0,1]
	v_mov_b32_e32 v104, v101
	v_pk_fma_f32 v[88:89], v[88:89], v[106:107], v[118:119] op_sel_hi:[1,0,1]
	v_mov_b32_e32 v106, v103
	v_pk_fma_f32 v[114:115], v[94:95], v[100:101], v[114:115] op_sel_hi:[1,1,0] neg_lo:[0,0,1] neg_hi:[0,0,1]
	v_pk_fma_f32 v[100:101], v[90:91], v[102:103], v[122:123] op_sel_hi:[1,1,0] neg_lo:[0,0,1] neg_hi:[0,0,1]
	v_pk_fma_f32 v[102:103], v[94:95], v[104:105], v[116:117] op_sel_hi:[1,1,0]
	v_pk_fma_f32 v[104:105], v[90:91], v[106:107], v[124:125] op_sel_hi:[1,1,0]
	v_sub_f32_e32 v88, v120, v118
	v_sub_f32_e32 v92, v110, v108
	v_mov_b32_e32 v90, v100
	v_mov_b32_e32 v94, v114
	v_mov_b32_e32 v91, v104
	v_mov_b32_e32 v95, v102

; DI unsigned pk2(float lo, float hi) { const f32x2 v = {lo, hi}; const hwbf16x2 b = __builtin_convertvector(v, hwbf16x2); return __builtin_bit_cast(unsigned, b); }
; DI float frsq(float x) { return __builtin_amdgcn_rsqf(x); }
;     DI void operator()(const f32x4 (&acc)[2][2][4][2], const Unit& u, int wr, int wc, int fr, int fq) const {
;     ...
;                 const int row = row0 + ai * HALF + m * 16;
;                 float rs = 1.f, rowacc = 0.f;
;                 if (mode == EPI_STORE || mode == EPI_Q) { if (rscale) rs = rscale[row]; }
;                 if (mode == EPI_SWIGLU) rs = frsq(rowsq[row] * (1.0f / DM) + 1e-6f);
; #pragma unroll
;                 for (int bj = 0; bj < 2; ++bj) {
;                     const int col = col0 + bj * HALF;
;                     f32x4 v0 = acc[ai][bj][m][0], v1 = acc[ai][bj][m][1];
;                     if (mode == EPI_STORE) {
;                         if (col < ncols) { v0 = v0 * rs; v1 = v1 * rs; u32x4 w; w.x = pk2(v0[0], v0[1]); w.y = pk2(v0[2], v0[3]); w.z = pk2(v1[0], v1[1]); w.w = pk2(v1[2], v1[3]);
;                             *(u32x4*)(O + (size_t)row * ldc + col) = w; }
;                     } else if (mode == EPI_Q) {
;                         const float sc = rs * qscale; v0 = v0 * sc; v1 = v1 * sc;
;                         const int c192 = col % 192;
;                         if (c192 >= 128) {
;                             const int i0 = (c192 - 128) >> 1, pos = row & (S_ - 1);
;                             const f32x4 cs = *(const f32x4*)(cosT + pos * 32 + i0), sn = *(const f32x4*)(sinT + pos * 32 + i0);
;                             float a, b;
;                             a = v0[0]; b = v0[1]; v0[0] = a * cs[0] - b * sn[0]; v0[1] = a * sn[0] + b * cs[0];
;                             a = v0[2]; b = v0[3]; v0[2] = a * cs[1] - b * sn[1]; v0[3] = a * sn[1] + b * cs[1];
;                             a = v1[0]; b = v1[1]; v1[0] = a * cs[2] - b * sn[2]; v1[1] = a * sn[2] + b * cs[2];
;                             a = v1[2]; b = v1[3]; v1[2] = a * cs[3] - b * sn[3]; v1[3] = a * sn[3] + b * cs[3];
;                         }
;                         u32x4 w; w.x = pk2(v0[0], v0[1]); w.y = pk2(v0[2], v0[3]); w.z = pk2(v1[0], v1[1]); w.w = pk2(v1[2], v1[3]);
;                         *(u32x4*)(O + (size_t)row * ldc + col) = w;
.LBB0_358:
	s_or_b64 exec, exec, s[30:31]
	v_cvt_pk_bf16_f32 v84, v84, v85
	v_cvt_pk_bf16_f32 v85, v86, v87
	v_cvt_pk_bf16_f32 v87, v82, v83
	v_or_b32_e32 v82, 48, v150
	v_cvt_pk_bf16_f32 v86, v80, v81
	v_ashrrev_i32_e32 v83, 31, v82
	global_store_dwordx4 v[88:89], v[84:87], off offset:256
	v_lshl_add_u64 v[80:81], v[82:83], 2, s[18:19]
	v_mov_b32_e32 v80, v239
	v_lshlrev_b32_e32 v81, 5, v82
	v_and_b32_e32 v81, 0x3ffe0, v81
	v_lshlrev_b32_e32 v136, 2, v81
	v_mul_f32_e32 v80, 0x3dd53b94, v80
	v_pk_mul_f32 v[78:79], v[78:79], v[80:81] op_sel_hi:[1,0]
	v_pk_mul_f32 v[76:77], v[76:77], v[80:81] op_sel_hi:[1,0]
	v_pk_mul_f32 v[74:75], v[74:75], v[80:81] op_sel_hi:[1,0]
	v_pk_mul_f32 v[72:73], v[72:73], v[80:81] op_sel_hi:[1,0]
	s_and_saveexec_b64 s[30:31], vcc
	s_cbranch_execz .LBB0_360
	v_mov_b32_e32 v149, v137
	v_lshl_add_u64 v[84:85], s[10:11], 0, v[136:137]
	v_lshlrev_b64 v[86:87], 2, v[148:149]
	v_lshl_add_u64 v[88:89], v[84:85], 0, v[86:87]
	v_lshl_add_u64 v[84:85], s[14:15], 0, v[136:137]
	v_lshl_add_u64 v[84:85], v[84:85], 0, v[86:87]
	global_load_dwordx4 v[84:87], v[84:85], off
	s_nop 0
	global_load_dwordx4 v[88:91], v[88:89], off
	s_waitcnt vmcnt(1)
	v_pk_mul_f32 v[92:93], v[76:77], v[84:85] op_sel:[1,0] op_sel_hi:[0,0]
	v_pk_mul_f32 v[100:101], v[72:73], v[86:87] op_sel:[1,0] op_sel_hi:[0,0]
	s_waitcnt vmcnt(0)
	v_pk_mul_f32 v[94:95], v[76:77], v[88:89]
	v_mov_b32_e32 v84, v89
	v_mul_f32_e32 v96, v79, v85
	v_mul_f32_e32 v98, v79, v89
	v_pk_mul_f32 v[102:103], v[72:73], v[90:91]
	v_mov_b32_e32 v86, v91
	v_mul_f32_e32 v104, v75, v87
	v_mul_f32_e32 v106, v75, v91
	v_pk_fma_f32 v[76:77], v[76:77], v[88:89], v[92:93] op_sel_hi:[1,0,1]
	v_mov_b32_e32 v88, v85
	v_pk_fma_f32 v[72:73], v[72:73], v[90:91], v[100:101] op_sel_hi:[1,0,1]
	v_mov_b32_e32 v90, v87
	v_pk_fma_f32 v[96:97], v[78:79], v[84:85], v[96:97] op_sel_hi:[1,1,0] neg_lo:[0,0,1] neg_hi:[0,0,1]
	v_pk_fma_f32 v[84:85], v[74:75], v[86:87], v[104:105] op_sel_hi:[1,1,0] neg_lo:[0,0,1] neg_hi:[0,0,1]
	v_pk_fma_f32 v[86:87], v[78:79], v[88:89], v[98:99] op_sel_hi:[1,1,0]
	v_pk_fma_f32 v[88:89], v[74:75], v[90:91], v[106:107] op_sel_hi:[1,1,0]
	v_sub_f32_e32 v72, v102, v100
	v_sub_f32_e32 v76, v94, v92
	v_mov_b32_e32 v74, v84
	v_mov_b32_e32 v78, v96
	v_mov_b32_e32 v75, v88
	v_mov_b32_e32 v79, v86

; DI unsigned pk2(float lo, float hi) { const f32x2 v = {lo, hi}; const hwbf16x2 b = __builtin_convertvector(v, hwbf16x2); return __builtin_bit_cast(unsigned, b); }
; DI float frsq(float x) { return __builtin_amdgcn_rsqf(x); }
;     DI void operator()(const f32x4 (&acc)[2][2][4][2], const Unit& u, int wr, int wc, int fr, int fq) const {
;     ...
;                 const int row = row0 + ai * HALF + m * 16;
;                 float rs = 1.f, rowacc = 0.f;
;                 if (mode == EPI_STORE || mode == EPI_Q) { if (rscale) rs = rscale[row]; }
;                 if (mode == EPI_SWIGLU) rs = frsq(rowsq[row] * (1.0f / DM) + 1e-6f);
; #pragma unroll
;                 for (int bj = 0; bj < 2; ++bj) {
;                     const int col = col0 + bj * HALF;
;                     f32x4 v0 = acc[ai][bj][m][0], v1 = acc[ai][bj][m][1];
;                     if (mode == EPI_STORE) {
;                         if (col < ncols) { v0 = v0 * rs; v1 = v1 * rs; u32x4 w; w.x = pk2(v0[0], v0[1]); w.y = pk2(v0[2], v0[3]); w.z = pk2(v1[0], v1[1]); w.w = pk2(v1[2], v1[3]);
;                             *(u32x4*)(O + (size_t)row * ldc + col) = w; }
;                     } else if (mode == EPI_Q) {
;                         const float sc = rs * qscale; v0 = v0 * sc; v1 = v1 * sc;
;                         const int c192 = col % 192;
;                         if (c192 >= 128) {
;                             const int i0 = (c192 - 128) >> 1, pos = row & (S_ - 1);
;                             const f32x4 cs = *(const f32x4*)(cosT + pos * 32 + i0), sn = *(const f32x4*)(sinT + pos * 32 + i0);
;                             float a, b;
;                             a = v0[0]; b = v0[1]; v0[0] = a * cs[0] - b * sn[0]; v0[1] = a * sn[0] + b * cs[0];
;                             a = v0[2]; b = v0[3]; v0[2] = a * cs[1] - b * sn[1]; v0[3] = a * sn[1] + b * cs[1];
;                             a = v1[0]; b = v1[1]; v1[0] = a * cs[2] - b * sn[2]; v1[1] = a * sn[2] + b * cs[2];
;                             a = v1[2]; b = v1[3]; v1[2] = a * cs[3] - b * sn[3]; v1[3] = a * sn[3] + b * cs[3];
;                         }
;                         u32x4 w; w.x = pk2(v0[0], v0[1]); w.y = pk2(v0[2], v0[3]); w.z = pk2(v1[0], v1[1]); w.w = pk2(v1[2], v1[3]);
;                         *(u32x4*)(O + (size_t)row * ldc + col) = w;
.LBB0_362:
	s_or_b64 exec, exec, s[30:31]
	v_cvt_pk_bf16_f32 v68, v68, v69
	v_cvt_pk_bf16_f32 v69, v70, v71
	v_cvt_pk_bf16_f32 v70, v64, v65
	v_cvt_pk_bf16_f32 v71, v66, v67
	global_store_dwordx4 v[72:73], v[68:71], off offset:256
	v_mov_b32_e32 v64, v240
	v_add_u32_e32 v66, 0x80, v150
	v_lshlrev_b32_e32 v65, 5, v66
	v_and_b32_e32 v65, 0x3f9e0, v65
	v_lshlrev_b32_e32 v136, 2, v65
	v_mul_f32_e32 v64, 0x3dd53b94, v64
	v_pk_mul_f32 v[62:63], v[62:63], v[64:65] op_sel_hi:[1,0]
	v_pk_mul_f32 v[60:61], v[60:61], v[64:65] op_sel_hi:[1,0]
	v_pk_mul_f32 v[58:59], v[58:59], v[64:65] op_sel_hi:[1,0]
	v_pk_mul_f32 v[56:57], v[56:57], v[64:65] op_sel_hi:[1,0]
	s_and_saveexec_b64 s[30:31], vcc
	s_cbranch_execz .LBB0_364
	v_mov_b32_e32 v149, v137
	v_lshl_add_u64 v[68:69], s[10:11], 0, v[136:137]
	v_lshlrev_b64 v[70:71], 2, v[148:149]
	v_lshl_add_u64 v[72:73], v[68:69], 0, v[70:71]
	v_lshl_add_u64 v[68:69], s[14:15], 0, v[136:137]
	v_lshl_add_u64 v[68:69], v[68:69], 0, v[70:71]
	global_load_dwordx4 v[68:71], v[68:69], off
	s_nop 0
	global_load_dwordx4 v[72:75], v[72:73], off
	s_waitcnt vmcnt(1)
	v_pk_mul_f32 v[76:77], v[60:61], v[68:69] op_sel:[1,0] op_sel_hi:[0,0]
	v_pk_mul_f32 v[84:85], v[56:57], v[70:71] op_sel:[1,0] op_sel_hi:[0,0]
	s_waitcnt vmcnt(0)
	v_pk_mul_f32 v[78:79], v[60:61], v[72:73]
	v_mov_b32_e32 v68, v73
	v_mul_f32_e32 v80, v63, v69
	v_mul_f32_e32 v82, v63, v73
	v_pk_mul_f32 v[86:87], v[56:57], v[74:75]
	v_mov_b32_e32 v70, v75
	v_mul_f32_e32 v88, v59, v71
	v_mul_f32_e32 v90, v59, v75
	v_pk_fma_f32 v[60:61], v[60:61], v[72:73], v[76:77] op_sel_hi:[1,0,1]
	v_mov_b32_e32 v72, v69
	v_pk_fma_f32 v[56:57], v[56:57], v[74:75], v[84:85] op_sel_hi:[1,0,1]
	v_mov_b32_e32 v74, v71
	v_pk_fma_f32 v[80:81], v[62:63], v[68:69], v[80:81] op_sel_hi:[1,1,0] neg_lo:[0,0,1] neg_hi:[0,0,1]
	v_pk_fma_f32 v[68:69], v[58:59], v[70:71], v[88:89] op_sel_hi:[1,1,0] neg_lo:[0,0,1] neg_hi:[0,0,1]
	v_pk_fma_f32 v[70:71], v[62:63], v[72:73], v[82:83] op_sel_hi:[1,1,0]
	v_pk_fma_f32 v[72:73], v[58:59], v[74:75], v[90:91] op_sel_hi:[1,1,0]
	v_sub_f32_e32 v56, v86, v84
	v_sub_f32_e32 v60, v78, v76
	v_mov_b32_e32 v58, v68
	v_mov_b32_e32 v62, v80
	v_mov_b32_e32 v59, v72
	v_mov_b32_e32 v63, v70

; DI unsigned pk2(float lo, float hi) { const f32x2 v = {lo, hi}; const hwbf16x2 b = __builtin_convertvector(v, hwbf16x2); return __builtin_bit_cast(unsigned, b); }
; DI float frsq(float x) { return __builtin_amdgcn_rsqf(x); }
;     DI void operator()(const f32x4 (&acc)[2][2][4][2], const Unit& u, int wr, int wc, int fr, int fq) const {
;     ...
;                 const int row = row0 + ai * HALF + m * 16;
;                 float rs = 1.f, rowacc = 0.f;
;                 if (mode == EPI_STORE || mode == EPI_Q) { if (rscale) rs = rscale[row]; }
;                 if (mode == EPI_SWIGLU) rs = frsq(rowsq[row] * (1.0f / DM) + 1e-6f);
; #pragma unroll
;                 for (int bj = 0; bj < 2; ++bj) {
;                     const int col = col0 + bj * HALF;
;                     f32x4 v0 = acc[ai][bj][m][0], v1 = acc[ai][bj][m][1];
;                     if (mode == EPI_STORE) {
;                         if (col < ncols) { v0 = v0 * rs; v1 = v1 * rs; u32x4 w; w.x = pk2(v0[0], v0[1]); w.y = pk2(v0[2], v0[3]); w.z = pk2(v1[0], v1[1]); w.w = pk2(v1[2], v1[3]);
;                             *(u32x4*)(O + (size_t)row * ldc + col) = w; }
;                     } else if (mode == EPI_Q) {
;                         const float sc = rs * qscale; v0 = v0 * sc; v1 = v1 * sc;
;                         const int c192 = col % 192;
;                         if (c192 >= 128) {
;                             const int i0 = (c192 - 128) >> 1, pos = row & (S_ - 1);
;                             const f32x4 cs = *(const f32x4*)(cosT + pos * 32 + i0), sn = *(const f32x4*)(sinT + pos * 32 + i0);
;                             float a, b;
;                             a = v0[0]; b = v0[1]; v0[0] = a * cs[0] - b * sn[0]; v0[1] = a * sn[0] + b * cs[0];
;                             a = v0[2]; b = v0[3]; v0[2] = a * cs[1] - b * sn[1]; v0[3] = a * sn[1] + b * cs[1];
;                             a = v1[0]; b = v1[1]; v1[0] = a * cs[2] - b * sn[2]; v1[1] = a * sn[2] + b * cs[2];
;                             a = v1[2]; b = v1[3]; v1[2] = a * cs[3] - b * sn[3]; v1[3] = a * sn[3] + b * cs[3];
;                         }
;                         u32x4 w; w.x = pk2(v0[0], v0[1]); w.y = pk2(v0[2], v0[3]); w.z = pk2(v1[0], v1[1]); w.w = pk2(v1[2], v1[3]);
;                         *(u32x4*)(O + (size_t)row * ldc + col) = w;
.LBB0_366:
	s_or_b64 exec, exec, s[30:31]
	v_cvt_pk_bf16_f32 v52, v52, v53
	v_cvt_pk_bf16_f32 v53, v54, v55
	v_cvt_pk_bf16_f32 v54, v48, v49
	v_cvt_pk_bf16_f32 v55, v50, v51
	global_store_dwordx4 v[56:57], v[52:55], off offset:256
	v_mov_b32_e32 v48, v241
	v_add_u32_e32 v50, 0x90, v150
	v_lshlrev_b32_e32 v49, 5, v50
	v_and_b32_e32 v49, 0x3fbe0, v49
	v_lshlrev_b32_e32 v136, 2, v49
	v_mul_f32_e32 v48, 0x3dd53b94, v48
	v_pk_mul_f32 v[46:47], v[46:47], v[48:49] op_sel_hi:[1,0]
	v_pk_mul_f32 v[44:45], v[44:45], v[48:49] op_sel_hi:[1,0]
	v_pk_mul_f32 v[42:43], v[42:43], v[48:49] op_sel_hi:[1,0]
	v_pk_mul_f32 v[40:41], v[40:41], v[48:49] op_sel_hi:[1,0]
	s_and_saveexec_b64 s[30:31], vcc
	s_cbranch_execz .LBB0_368
	v_mov_b32_e32 v149, v137
	v_lshl_add_u64 v[52:53], s[10:11], 0, v[136:137]
	v_lshlrev_b64 v[54:55], 2, v[148:149]
	v_lshl_add_u64 v[56:57], v[52:53], 0, v[54:55]
	v_lshl_add_u64 v[52:53], s[14:15], 0, v[136:137]
	v_lshl_add_u64 v[52:53], v[52:53], 0, v[54:55]
	global_load_dwordx4 v[52:55], v[52:53], off
	s_nop 0
	global_load_dwordx4 v[56:59], v[56:57], off
	s_waitcnt vmcnt(1)
	v_pk_mul_f32 v[60:61], v[44:45], v[52:53] op_sel:[1,0] op_sel_hi:[0,0]
	v_pk_mul_f32 v[68:69], v[40:41], v[54:55] op_sel:[1,0] op_sel_hi:[0,0]
	s_waitcnt vmcnt(0)
	v_pk_mul_f32 v[62:63], v[44:45], v[56:57]
	v_mov_b32_e32 v52, v57
	v_mul_f32_e32 v64, v47, v53
	v_mul_f32_e32 v66, v47, v57
	v_pk_mul_f32 v[70:71], v[40:41], v[58:59]
	v_mov_b32_e32 v54, v59
	v_mul_f32_e32 v72, v43, v55
	v_mul_f32_e32 v74, v43, v59
	v_pk_fma_f32 v[44:45], v[44:45], v[56:57], v[60:61] op_sel_hi:[1,0,1]
	v_mov_b32_e32 v56, v53
	v_pk_fma_f32 v[40:41], v[40:41], v[58:59], v[68:69] op_sel_hi:[1,0,1]
	v_mov_b32_e32 v58, v55
	v_pk_fma_f32 v[64:65], v[46:47], v[52:53], v[64:65] op_sel_hi:[1,1,0] neg_lo:[0,0,1] neg_hi:[0,0,1]
	v_pk_fma_f32 v[52:53], v[42:43], v[54:55], v[72:73] op_sel_hi:[1,1,0] neg_lo:[0,0,1] neg_hi:[0,0,1]
	v_pk_fma_f32 v[54:55], v[46:47], v[56:57], v[66:67] op_sel_hi:[1,1,0]
	v_pk_fma_f32 v[56:57], v[42:43], v[58:59], v[74:75] op_sel_hi:[1,1,0]
	v_sub_f32_e32 v40, v70, v68
	v_sub_f32_e32 v44, v62, v60
	v_mov_b32_e32 v42, v52
	v_mov_b32_e32 v46, v64
	v_mov_b32_e32 v43, v56
	v_mov_b32_e32 v47, v54

; DI unsigned pk2(float lo, float hi) { const f32x2 v = {lo, hi}; const hwbf16x2 b = __builtin_convertvector(v, hwbf16x2); return __builtin_bit_cast(unsigned, b); }
; DI float frsq(float x) { return __builtin_amdgcn_rsqf(x); }
;     DI void operator()(const f32x4 (&acc)[2][2][4][2], const Unit& u, int wr, int wc, int fr, int fq) const {
;     ...
;                 const int row = row0 + ai * HALF + m * 16;
;                 float rs = 1.f, rowacc = 0.f;
;                 if (mode == EPI_STORE || mode == EPI_Q) { if (rscale) rs = rscale[row]; }
;                 if (mode == EPI_SWIGLU) rs = frsq(rowsq[row] * (1.0f / DM) + 1e-6f);
; #pragma unroll
;                 for (int bj = 0; bj < 2; ++bj) {
;                     const int col = col0 + bj * HALF;
;                     f32x4 v0 = acc[ai][bj][m][0], v1 = acc[ai][bj][m][1];
;                     if (mode == EPI_STORE) {
;                         if (col < ncols) { v0 = v0 * rs; v1 = v1 * rs; u32x4 w; w.x = pk2(v0[0], v0[1]); w.y = pk2(v0[2], v0[3]); w.z = pk2(v1[0], v1[1]); w.w = pk2(v1[2], v1[3]);
;                             *(u32x4*)(O + (size_t)row * ldc + col) = w; }
;                     } else if (mode == EPI_Q) {
;                         const float sc = rs * qscale; v0 = v0 * sc; v1 = v1 * sc;
;                         const int c192 = col % 192;
;                         if (c192 >= 128) {
;                             const int i0 = (c192 - 128) >> 1, pos = row & (S_ - 1);
;                             const f32x4 cs = *(const f32x4*)(cosT + pos * 32 + i0), sn = *(const f32x4*)(sinT + pos * 32 + i0);
;                             float a, b;
;                             a = v0[0]; b = v0[1]; v0[0] = a * cs[0] - b * sn[0]; v0[1] = a * sn[0] + b * cs[0];
;                             a = v0[2]; b = v0[3]; v0[2] = a * cs[1] - b * sn[1]; v0[3] = a * sn[1] + b * cs[1];
;                             a = v1[0]; b = v1[1]; v1[0] = a * cs[2] - b * sn[2]; v1[1] = a * sn[2] + b * cs[2];
;                             a = v1[2]; b = v1[3]; v1[2] = a * cs[3] - b * sn[3]; v1[3] = a * sn[3] + b * cs[3];
;                         }
;                         u32x4 w; w.x = pk2(v0[0], v0[1]); w.y = pk2(v0[2], v0[3]); w.z = pk2(v1[0], v1[1]); w.w = pk2(v1[2], v1[3]);
;                         *(u32x4*)(O + (size_t)row * ldc + col) = w;
.LBB0_370:
	s_or_b64 exec, exec, s[30:31]
	v_cvt_pk_bf16_f32 v36, v36, v37
	v_cvt_pk_bf16_f32 v37, v38, v39
	v_cvt_pk_bf16_f32 v38, v32, v33
	v_cvt_pk_bf16_f32 v39, v34, v35
	global_store_dwordx4 v[40:41], v[36:39], off offset:256
	v_mov_b32_e32 v32, v242
	v_add_u32_e32 v34, 0xa0, v150
	v_lshlrev_b32_e32 v33, 5, v34
	v_and_b32_e32 v33, 0x3fde0, v33
	v_lshlrev_b32_e32 v136, 2, v33
	v_mul_f32_e32 v32, 0x3dd53b94, v32
	v_pk_mul_f32 v[30:31], v[30:31], v[32:33] op_sel_hi:[1,0]
	v_pk_mul_f32 v[28:29], v[28:29], v[32:33] op_sel_hi:[1,0]
	v_pk_mul_f32 v[26:27], v[26:27], v[32:33] op_sel_hi:[1,0]
	v_pk_mul_f32 v[24:25], v[24:25], v[32:33] op_sel_hi:[1,0]
	s_and_saveexec_b64 s[30:31], vcc
	s_cbranch_execz .LBB0_372
	v_mov_b32_e32 v149, v137
	v_lshl_add_u64 v[36:37], s[10:11], 0, v[136:137]
	v_lshlrev_b64 v[38:39], 2, v[148:149]
	v_lshl_add_u64 v[40:41], v[36:37], 0, v[38:39]
	v_lshl_add_u64 v[36:37], s[14:15], 0, v[136:137]
	v_lshl_add_u64 v[36:37], v[36:37], 0, v[38:39]
	global_load_dwordx4 v[36:39], v[36:37], off
	s_nop 0
	global_load_dwordx4 v[40:43], v[40:41], off
	s_waitcnt vmcnt(1)
	v_pk_mul_f32 v[44:45], v[28:29], v[36:37] op_sel:[1,0] op_sel_hi:[0,0]
	v_pk_mul_f32 v[52:53], v[24:25], v[38:39] op_sel:[1,0] op_sel_hi:[0,0]
	s_waitcnt vmcnt(0)
	v_pk_mul_f32 v[46:47], v[28:29], v[40:41]
	v_mov_b32_e32 v36, v41
	v_mul_f32_e32 v48, v31, v37
	v_mul_f32_e32 v50, v31, v41
	v_pk_mul_f32 v[54:55], v[24:25], v[42:43]
	v_mov_b32_e32 v38, v43
	v_mul_f32_e32 v56, v27, v39
	v_mul_f32_e32 v58, v27, v43
	v_pk_fma_f32 v[28:29], v[28:29], v[40:41], v[44:45] op_sel_hi:[1,0,1]
	v_mov_b32_e32 v40, v37
	v_pk_fma_f32 v[24:25], v[24:25], v[42:43], v[52:53] op_sel_hi:[1,0,1]
	v_mov_b32_e32 v42, v39
	v_pk_fma_f32 v[48:49], v[30:31], v[36:37], v[48:49] op_sel_hi:[1,1,0] neg_lo:[0,0,1] neg_hi:[0,0,1]
	v_pk_fma_f32 v[36:37], v[26:27], v[38:39], v[56:57] op_sel_hi:[1,1,0] neg_lo:[0,0,1] neg_hi:[0,0,1]
	v_pk_fma_f32 v[38:39], v[30:31], v[40:41], v[50:51] op_sel_hi:[1,1,0]
	v_pk_fma_f32 v[40:41], v[26:27], v[42:43], v[58:59] op_sel_hi:[1,1,0]
	v_sub_f32_e32 v24, v54, v52
	v_sub_f32_e32 v28, v46, v44
	v_mov_b32_e32 v26, v36
	v_mov_b32_e32 v30, v48
	v_mov_b32_e32 v27, v40
	v_mov_b32_e32 v31, v38

; DI unsigned pk2(float lo, float hi) { const f32x2 v = {lo, hi}; const hwbf16x2 b = __builtin_convertvector(v, hwbf16x2); return __builtin_bit_cast(unsigned, b); }
; DI float frsq(float x) { return __builtin_amdgcn_rsqf(x); }
;     DI void operator()(const f32x4 (&acc)[2][2][4][2], const Unit& u, int wr, int wc, int fr, int fq) const {
;     ...
;                 const int row = row0 + ai * HALF + m * 16;
;                 float rs = 1.f, rowacc = 0.f;
;                 if (mode == EPI_STORE || mode == EPI_Q) { if (rscale) rs = rscale[row]; }
;                 if (mode == EPI_SWIGLU) rs = frsq(rowsq[row] * (1.0f / DM) + 1e-6f);
; #pragma unroll
;                 for (int bj = 0; bj < 2; ++bj) {
;                     const int col = col0 + bj * HALF;
;                     f32x4 v0 = acc[ai][bj][m][0], v1 = acc[ai][bj][m][1];
;                     if (mode == EPI_STORE) {
;                         if (col < ncols) { v0 = v0 * rs; v1 = v1 * rs; u32x4 w; w.x = pk2(v0[0], v0[1]); w.y = pk2(v0[2], v0[3]); w.z = pk2(v1[0], v1[1]); w.w = pk2(v1[2], v1[3]);
;                             *(u32x4*)(O + (size_t)row * ldc + col) = w; }
;                     } else if (mode == EPI_Q) {
;                         const float sc = rs * qscale; v0 = v0 * sc; v1 = v1 * sc;
;                         const int c192 = col % 192;
;                         if (c192 >= 128) {
;                             const int i0 = (c192 - 128) >> 1, pos = row & (S_ - 1);
;                             const f32x4 cs = *(const f32x4*)(cosT + pos * 32 + i0), sn = *(const f32x4*)(sinT + pos * 32 + i0);
;                             float a, b;
;                             a = v0[0]; b = v0[1]; v0[0] = a * cs[0] - b * sn[0]; v0[1] = a * sn[0] + b * cs[0];
;                             a = v0[2]; b = v0[3]; v0[2] = a * cs[1] - b * sn[1]; v0[3] = a * sn[1] + b * cs[1];
;                             a = v1[0]; b = v1[1]; v1[0] = a * cs[2] - b * sn[2]; v1[1] = a * sn[2] + b * cs[2];
;                             a = v1[2]; b = v1[3]; v1[2] = a * cs[3] - b * sn[3]; v1[3] = a * sn[3] + b * cs[3];
;                         }
;                         u32x4 w; w.x = pk2(v0[0], v0[1]); w.y = pk2(v0[2], v0[3]); w.z = pk2(v1[0], v1[1]); w.w = pk2(v1[2], v1[3]);
;                         *(u32x4*)(O + (size_t)row * ldc + col) = w;
.LBB0_374:
	s_or_b64 exec, exec, s[30:31]
	v_cvt_pk_bf16_f32 v20, v20, v21
	v_cvt_pk_bf16_f32 v21, v22, v23
	v_cvt_pk_bf16_f32 v22, v16, v17
	v_cvt_pk_bf16_f32 v23, v18, v19
	global_store_dwordx4 v[24:25], v[20:23], off offset:256
	v_mov_b32_e32 v16, v243
	v_add_u32_e32 v18, 0xb0, v150
	v_lshlrev_b32_e32 v17, 5, v18
	v_and_b32_e32 v17, 0x3ffe0, v17
	v_lshlrev_b32_e32 v136, 2, v17
	v_mul_f32_e32 v16, 0x3dd53b94, v16
	v_pk_mul_f32 v[14:15], v[14:15], v[16:17] op_sel_hi:[1,0]
	v_pk_mul_f32 v[12:13], v[12:13], v[16:17] op_sel_hi:[1,0]
	v_pk_mul_f32 v[10:11], v[10:11], v[16:17] op_sel_hi:[1,0]
	v_pk_mul_f32 v[8:9], v[8:9], v[16:17] op_sel_hi:[1,0]
	s_and_saveexec_b64 s[30:31], vcc
	s_cbranch_execz .LBB0_376
	v_mov_b32_e32 v149, v137
	v_lshl_add_u64 v[20:21], s[10:11], 0, v[136:137]
	v_lshlrev_b64 v[22:23], 2, v[148:149]
	v_lshl_add_u64 v[24:25], v[20:21], 0, v[22:23]
	v_lshl_add_u64 v[20:21], s[14:15], 0, v[136:137]
	v_lshl_add_u64 v[20:21], v[20:21], 0, v[22:23]
	global_load_dwordx4 v[20:23], v[20:21], off
	s_nop 0
	global_load_dwordx4 v[24:27], v[24:25], off
	s_waitcnt vmcnt(1)
	v_pk_mul_f32 v[28:29], v[12:13], v[20:21] op_sel:[1,0] op_sel_hi:[0,0]
	v_pk_mul_f32 v[36:37], v[8:9], v[22:23] op_sel:[1,0] op_sel_hi:[0,0]
	s_waitcnt vmcnt(0)
	v_pk_mul_f32 v[30:31], v[12:13], v[24:25]
	v_mov_b32_e32 v20, v25
	v_mul_f32_e32 v32, v15, v21
	v_mul_f32_e32 v34, v15, v25
	v_pk_mul_f32 v[38:39], v[8:9], v[26:27]
	v_mov_b32_e32 v22, v27
	v_mul_f32_e32 v40, v11, v23
	v_mul_f32_e32 v42, v11, v27
	v_pk_fma_f32 v[12:13], v[12:13], v[24:25], v[28:29] op_sel_hi:[1,0,1]
	v_mov_b32_e32 v24, v21
	v_pk_fma_f32 v[8:9], v[8:9], v[26:27], v[36:37] op_sel_hi:[1,0,1]
	v_mov_b32_e32 v26, v23
	v_pk_fma_f32 v[32:33], v[14:15], v[20:21], v[32:33] op_sel_hi:[1,1,0] neg_lo:[0,0,1] neg_hi:[0,0,1]
	v_pk_fma_f32 v[20:21], v[10:11], v[22:23], v[40:41] op_sel_hi:[1,1,0] neg_lo:[0,0,1] neg_hi:[0,0,1]
	v_pk_fma_f32 v[22:23], v[14:15], v[24:25], v[34:35] op_sel_hi:[1,1,0]
	v_pk_fma_f32 v[24:25], v[10:11], v[26:27], v[42:43] op_sel_hi:[1,1,0]
	v_sub_f32_e32 v8, v38, v36
	v_sub_f32_e32 v12, v30, v28
	v_mov_b32_e32 v10, v20
	v_mov_b32_e32 v14, v32
	v_mov_b32_e32 v11, v24
	v_mov_b32_e32 v15, v22

; DI unsigned pk2(float lo, float hi) { const f32x2 v = {lo, hi}; const hwbf16x2 b = __builtin_convertvector(v, hwbf16x2); return __builtin_bit_cast(unsigned, b); }
; DI float frsq(float x) { return __builtin_amdgcn_rsqf(x); }
;     DI void operator()(const f32x4 (&acc)[2][2][4][2], const Unit& u, int wr, int wc, int fr, int fq) const {
;     ...
;                 const int row = row0 + ai * HALF + m * 16;
;                 float rs = 1.f, rowacc = 0.f;
;                 if (mode == EPI_STORE || mode == EPI_Q) { if (rscale) rs = rscale[row]; }
;                 if (mode == EPI_SWIGLU) rs = frsq(rowsq[row] * (1.0f / DM) + 1e-6f);
; #pragma unroll
;                 for (int bj = 0; bj < 2; ++bj) {
;                     const int col = col0 + bj * HALF;
;                     f32x4 v0 = acc[ai][bj][m][0], v1 = acc[ai][bj][m][1];
;                     if (mode == EPI_STORE) {
;                         if (col < ncols) { v0 = v0 * rs; v1 = v1 * rs; u32x4 w; w.x = pk2(v0[0], v0[1]); w.y = pk2(v0[2], v0[3]); w.z = pk2(v1[0], v1[1]); w.w = pk2(v1[2], v1[3]);
;                             *(u32x4*)(O + (size_t)row * ldc + col) = w; }
.LBB0_406:
	v_lshl_add_u32 v142, s73, 8, v150
	v_ashrrev_i32_e32 v143, 31, v142
	v_lshl_add_u64 v[144:145], v[142:143], 2, s[10:11]
	global_load_dword v236, v[144:145], off
	global_load_dword v237, v[144:145], off offset:64
	global_load_dword v238, v[144:145], off offset:128
	global_load_dword v239, v[144:145], off offset:192
	global_load_dword v240, v[144:145], off offset:512
	global_load_dword v241, v[144:145], off offset:576
	global_load_dword v242, v[144:145], off offset:640
	global_load_dword v243, v[144:145], off offset:704
	v_lshl_or_b32 v140, s26, 8, v152
	v_lshlrev_b64 v[146:147], 11, v[142:143]
	v_cmp_gt_i32_e32 vcc, s48, v140
	v_ashrrev_i32_e32 v141, 31, v140
	v_lshl_add_u64 v[146:147], s[50:51], 0, v[146:147]
	s_waitcnt vmcnt(0)
	v_mov_b32_e32 v148, v236
	v_mov_b32_e32 v149, v148
	s_and_saveexec_b64 s[6:7], vcc
	s_cbranch_execz .LBB0_408
	v_mov_b32_e32 v156, v148
	v_mov_b32_e32 v157, v148
	v_pk_mul_f32 v[126:127], v[126:127], v[156:157]
	v_pk_mul_f32 v[124:125], v[124:125], v[148:149]
	v_pk_mul_f32 v[156:157], v[122:123], v[156:157]
	v_pk_mul_f32 v[122:123], v[120:121], v[148:149]
	v_cvt_pk_bf16_f32 v120, v124, v125
	v_cvt_pk_bf16_f32 v121, v126, v127
	v_cvt_pk_bf16_f32 v122, v122, v123
	v_cvt_pk_bf16_f32 v123, v156, v157
	v_lshl_add_u64 v[124:125], v[140:141], 1, v[146:147]
	global_store_dwordx4 v[124:125], v[120:123], off

; DI unsigned pk2(float lo, float hi) { const f32x2 v = {lo, hi}; const hwbf16x2 b = __builtin_convertvector(v, hwbf16x2); return __builtin_bit_cast(unsigned, b); }
; DI float frsq(float x) { return __builtin_amdgcn_rsqf(x); }
;     DI void operator()(const f32x4 (&acc)[2][2][4][2], const Unit& u, int wr, int wc, int fr, int fq) const {
;     ...
;                 const int row = row0 + ai * HALF + m * 16;
;                 float rs = 1.f, rowacc = 0.f;
;                 if (mode == EPI_STORE || mode == EPI_Q) { if (rscale) rs = rscale[row]; }
;                 if (mode == EPI_SWIGLU) rs = frsq(rowsq[row] * (1.0f / DM) + 1e-6f);
; #pragma unroll
;                 for (int bj = 0; bj < 2; ++bj) {
;                     const int col = col0 + bj * HALF;
;                     f32x4 v0 = acc[ai][bj][m][0], v1 = acc[ai][bj][m][1];
;                     if (mode == EPI_STORE) {
;                         if (col < ncols) { v0 = v0 * rs; v1 = v1 * rs; u32x4 w; w.x = pk2(v0[0], v0[1]); w.y = pk2(v0[2], v0[3]); w.z = pk2(v1[0], v1[1]); w.w = pk2(v1[2], v1[3]);
;                             *(u32x4*)(O + (size_t)row * ldc + col) = w; }
.LBB0_410:
	s_or_b64 exec, exec, s[26:27]
	s_nop 0
	v_or_b32_e32 v112, 16, v142
	v_ashrrev_i32_e32 v113, 31, v112
	v_lshl_add_u64 v[114:115], v[112:113], 2, s[10:11]
	v_mov_b32_e32 v114, v237
	v_lshlrev_b64 v[112:113], 11, v[112:113]
	v_lshl_add_u64 v[112:113], s[50:51], 0, v[112:113]
	v_mov_b32_e32 v115, v114
	s_and_saveexec_b64 s[26:27], vcc
	s_cbranch_execz .LBB0_412
	v_mov_b32_e32 v116, v114
	v_mov_b32_e32 v117, v114
	v_pk_mul_f32 v[110:111], v[110:111], v[116:117]
	v_pk_mul_f32 v[108:109], v[108:109], v[114:115]
	v_pk_mul_f32 v[116:117], v[106:107], v[116:117]
	v_pk_mul_f32 v[106:107], v[104:105], v[114:115]
	v_cvt_pk_bf16_f32 v104, v108, v109
	v_cvt_pk_bf16_f32 v105, v110, v111
	v_cvt_pk_bf16_f32 v106, v106, v107
	v_cvt_pk_bf16_f32 v107, v116, v117
	v_lshl_add_u64 v[108:109], v[140:141], 1, v[112:113]
	global_store_dwordx4 v[108:109], v[104:107], off

; DI unsigned pk2(float lo, float hi) { const f32x2 v = {lo, hi}; const hwbf16x2 b = __builtin_convertvector(v, hwbf16x2); return __builtin_bit_cast(unsigned, b); }
; DI float frsq(float x) { return __builtin_amdgcn_rsqf(x); }
;     DI void operator()(const f32x4 (&acc)[2][2][4][2], const Unit& u, int wr, int wc, int fr, int fq) const {
;     ...
;                 const int row = row0 + ai * HALF + m * 16;
;                 float rs = 1.f, rowacc = 0.f;
;                 if (mode == EPI_STORE || mode == EPI_Q) { if (rscale) rs = rscale[row]; }
;                 if (mode == EPI_SWIGLU) rs = frsq(rowsq[row] * (1.0f / DM) + 1e-6f);
; #pragma unroll
;                 for (int bj = 0; bj < 2; ++bj) {
;                     const int col = col0 + bj * HALF;
;                     f32x4 v0 = acc[ai][bj][m][0], v1 = acc[ai][bj][m][1];
;                     if (mode == EPI_STORE) {
;                         if (col < ncols) { v0 = v0 * rs; v1 = v1 * rs; u32x4 w; w.x = pk2(v0[0], v0[1]); w.y = pk2(v0[2], v0[3]); w.z = pk2(v1[0], v1[1]); w.w = pk2(v1[2], v1[3]);
;                             *(u32x4*)(O + (size_t)row * ldc + col) = w; }
.LBB0_414:
	s_or_b64 exec, exec, s[26:27]
	s_nop 0
	v_or_b32_e32 v96, 32, v142
	v_ashrrev_i32_e32 v97, 31, v96
	v_lshl_add_u64 v[98:99], v[96:97], 2, s[10:11]
	v_mov_b32_e32 v98, v238
	v_lshlrev_b64 v[96:97], 11, v[96:97]
	v_lshl_add_u64 v[96:97], s[50:51], 0, v[96:97]
	v_mov_b32_e32 v99, v98
	s_and_saveexec_b64 s[26:27], vcc
	s_cbranch_execz .LBB0_416
	v_mov_b32_e32 v100, v98
	v_mov_b32_e32 v101, v98
	v_pk_mul_f32 v[94:95], v[94:95], v[100:101]
	v_pk_mul_f32 v[92:93], v[92:93], v[98:99]
	v_pk_mul_f32 v[100:101], v[90:91], v[100:101]
	v_pk_mul_f32 v[90:91], v[88:89], v[98:99]
	v_cvt_pk_bf16_f32 v88, v92, v93
	v_cvt_pk_bf16_f32 v89, v94, v95
	v_cvt_pk_bf16_f32 v90, v90, v91
	v_cvt_pk_bf16_f32 v91, v100, v101
	v_lshl_add_u64 v[92:93], v[140:141], 1, v[96:97]
	global_store_dwordx4 v[92:93], v[88:91], off

; DI unsigned pk2(float lo, float hi) { const f32x2 v = {lo, hi}; const hwbf16x2 b = __builtin_convertvector(v, hwbf16x2); return __builtin_bit_cast(unsigned, b); }
; DI float frsq(float x) { return __builtin_amdgcn_rsqf(x); }
;     DI void operator()(const f32x4 (&acc)[2][2][4][2], const Unit& u, int wr, int wc, int fr, int fq) const {
;     ...
;                 const int row = row0 + ai * HALF + m * 16;
;                 float rs = 1.f, rowacc = 0.f;
;                 if (mode == EPI_STORE || mode == EPI_Q) { if (rscale) rs = rscale[row]; }
;                 if (mode == EPI_SWIGLU) rs = frsq(rowsq[row] * (1.0f / DM) + 1e-6f);
; #pragma unroll
;                 for (int bj = 0; bj < 2; ++bj) {
;                     const int col = col0 + bj * HALF;
;                     f32x4 v0 = acc[ai][bj][m][0], v1 = acc[ai][bj][m][1];
;                     if (mode == EPI_STORE) {
;                         if (col < ncols) { v0 = v0 * rs; v1 = v1 * rs; u32x4 w; w.x = pk2(v0[0], v0[1]); w.y = pk2(v0[2], v0[3]); w.z = pk2(v1[0], v1[1]); w.w = pk2(v1[2], v1[3]);
;                             *(u32x4*)(O + (size_t)row * ldc + col) = w; }
.LBB0_418:
	s_or_b64 exec, exec, s[26:27]
	s_nop 0
	v_or_b32_e32 v80, 48, v142
	v_ashrrev_i32_e32 v81, 31, v80
	v_lshl_add_u64 v[82:83], v[80:81], 2, s[10:11]
	v_mov_b32_e32 v82, v239
	v_lshlrev_b64 v[80:81], 11, v[80:81]
	v_lshl_add_u64 v[80:81], s[50:51], 0, v[80:81]
	v_mov_b32_e32 v83, v82
	s_and_saveexec_b64 s[26:27], vcc
	s_cbranch_execz .LBB0_420
	v_mov_b32_e32 v84, v82
	v_mov_b32_e32 v85, v82
	v_pk_mul_f32 v[78:79], v[78:79], v[84:85]
	v_pk_mul_f32 v[76:77], v[76:77], v[82:83]
	v_pk_mul_f32 v[84:85], v[74:75], v[84:85]
	v_pk_mul_f32 v[74:75], v[72:73], v[82:83]
	v_cvt_pk_bf16_f32 v72, v76, v77
	v_cvt_pk_bf16_f32 v73, v78, v79
	v_cvt_pk_bf16_f32 v74, v74, v75
	v_cvt_pk_bf16_f32 v75, v84, v85
	v_lshl_add_u64 v[76:77], v[140:141], 1, v[80:81]
	global_store_dwordx4 v[76:77], v[72:75], off

; DI unsigned pk2(float lo, float hi) { const f32x2 v = {lo, hi}; const hwbf16x2 b = __builtin_convertvector(v, hwbf16x2); return __builtin_bit_cast(unsigned, b); }
; DI float frsq(float x) { return __builtin_amdgcn_rsqf(x); }
;     DI void operator()(const f32x4 (&acc)[2][2][4][2], const Unit& u, int wr, int wc, int fr, int fq) const {
;     ...
;                 const int row = row0 + ai * HALF + m * 16;
;                 float rs = 1.f, rowacc = 0.f;
;                 if (mode == EPI_STORE || mode == EPI_Q) { if (rscale) rs = rscale[row]; }
;                 if (mode == EPI_SWIGLU) rs = frsq(rowsq[row] * (1.0f / DM) + 1e-6f);
; #pragma unroll
;                 for (int bj = 0; bj < 2; ++bj) {
;                     const int col = col0 + bj * HALF;
;                     f32x4 v0 = acc[ai][bj][m][0], v1 = acc[ai][bj][m][1];
;                     if (mode == EPI_STORE) {
;                         if (col < ncols) { v0 = v0 * rs; v1 = v1 * rs; u32x4 w; w.x = pk2(v0[0], v0[1]); w.y = pk2(v0[2], v0[3]); w.z = pk2(v1[0], v1[1]); w.w = pk2(v1[2], v1[3]);
;                             *(u32x4*)(O + (size_t)row * ldc + col) = w; }
.LBB0_422:
	s_or_b64 exec, exec, s[26:27]
	v_mov_b32_e32 v66, v240
	v_add_u32_e32 v64, 0x80, v142
	v_ashrrev_i32_e32 v65, 31, v64
	v_lshlrev_b64 v[64:65], 11, v[64:65]
	v_lshl_add_u64 v[64:65], s[50:51], 0, v[64:65]
	v_mov_b32_e32 v67, v66
	s_and_saveexec_b64 s[26:27], vcc
	s_cbranch_execz .LBB0_424
	v_mov_b32_e32 v68, v66
	v_mov_b32_e32 v69, v66
	v_pk_mul_f32 v[62:63], v[62:63], v[68:69]
	v_pk_mul_f32 v[60:61], v[60:61], v[66:67]
	v_pk_mul_f32 v[68:69], v[58:59], v[68:69]
	v_pk_mul_f32 v[58:59], v[56:57], v[66:67]
	v_cvt_pk_bf16_f32 v56, v60, v61
	v_cvt_pk_bf16_f32 v57, v62, v63
	v_cvt_pk_bf16_f32 v58, v58, v59
	v_cvt_pk_bf16_f32 v59, v68, v69
	v_lshl_add_u64 v[60:61], v[140:141], 1, v[64:65]
	global_store_dwordx4 v[60:61], v[56:59], off

; DI unsigned pk2(float lo, float hi) { const f32x2 v = {lo, hi}; const hwbf16x2 b = __builtin_convertvector(v, hwbf16x2); return __builtin_bit_cast(unsigned, b); }
; DI float frsq(float x) { return __builtin_amdgcn_rsqf(x); }
;     DI void operator()(const f32x4 (&acc)[2][2][4][2], const Unit& u, int wr, int wc, int fr, int fq) const {
;     ...
;                 const int row = row0 + ai * HALF + m * 16;
;                 float rs = 1.f, rowacc = 0.f;
;                 if (mode == EPI_STORE || mode == EPI_Q) { if (rscale) rs = rscale[row]; }
;                 if (mode == EPI_SWIGLU) rs = frsq(rowsq[row] * (1.0f / DM) + 1e-6f);
; #pragma unroll
;                 for (int bj = 0; bj < 2; ++bj) {
;                     const int col = col0 + bj * HALF;
;                     f32x4 v0 = acc[ai][bj][m][0], v1 = acc[ai][bj][m][1];
;                     if (mode == EPI_STORE) {
;                         if (col < ncols) { v0 = v0 * rs; v1 = v1 * rs; u32x4 w; w.x = pk2(v0[0], v0[1]); w.y = pk2(v0[2], v0[3]); w.z = pk2(v1[0], v1[1]); w.w = pk2(v1[2], v1[3]);
;                             *(u32x4*)(O + (size_t)row * ldc + col) = w; }
.LBB0_426:
	s_or_b64 exec, exec, s[26:27]
	v_mov_b32_e32 v50, v241
	v_add_u32_e32 v48, 0x90, v142
	v_ashrrev_i32_e32 v49, 31, v48
	v_lshlrev_b64 v[48:49], 11, v[48:49]
	v_lshl_add_u64 v[48:49], s[50:51], 0, v[48:49]
	v_mov_b32_e32 v51, v50
	s_and_saveexec_b64 s[26:27], vcc
	s_cbranch_execz .LBB0_428
	v_mov_b32_e32 v52, v50
	v_mov_b32_e32 v53, v50
	v_pk_mul_f32 v[46:47], v[46:47], v[52:53]
	v_pk_mul_f32 v[44:45], v[44:45], v[50:51]
	v_pk_mul_f32 v[52:53], v[42:43], v[52:53]
	v_pk_mul_f32 v[42:43], v[40:41], v[50:51]
	v_cvt_pk_bf16_f32 v40, v44, v45
	v_cvt_pk_bf16_f32 v41, v46, v47
	v_cvt_pk_bf16_f32 v42, v42, v43
	v_cvt_pk_bf16_f32 v43, v52, v53
	v_lshl_add_u64 v[44:45], v[140:141], 1, v[48:49]
	global_store_dwordx4 v[44:45], v[40:43], off

; DI unsigned pk2(float lo, float hi) { const f32x2 v = {lo, hi}; const hwbf16x2 b = __builtin_convertvector(v, hwbf16x2); return __builtin_bit_cast(unsigned, b); }
; DI float frsq(float x) { return __builtin_amdgcn_rsqf(x); }
;     DI void operator()(const f32x4 (&acc)[2][2][4][2], const Unit& u, int wr, int wc, int fr, int fq) const {
;     ...
;                 const int row = row0 + ai * HALF + m * 16;
;                 float rs = 1.f, rowacc = 0.f;
;                 if (mode == EPI_STORE || mode == EPI_Q) { if (rscale) rs = rscale[row]; }
;                 if (mode == EPI_SWIGLU) rs = frsq(rowsq[row] * (1.0f / DM) + 1e-6f);
; #pragma unroll
;                 for (int bj = 0; bj < 2; ++bj) {
;                     const int col = col0 + bj * HALF;
;                     f32x4 v0 = acc[ai][bj][m][0], v1 = acc[ai][bj][m][1];
;                     if (mode == EPI_STORE) {
;                         if (col < ncols) { v0 = v0 * rs; v1 = v1 * rs; u32x4 w; w.x = pk2(v0[0], v0[1]); w.y = pk2(v0[2], v0[3]); w.z = pk2(v1[0], v1[1]); w.w = pk2(v1[2], v1[3]);
;                             *(u32x4*)(O + (size_t)row * ldc + col) = w; }
.LBB0_430:
	s_or_b64 exec, exec, s[26:27]
	v_mov_b32_e32 v34, v242
	v_add_u32_e32 v32, 0xa0, v142
	v_ashrrev_i32_e32 v33, 31, v32
	v_lshlrev_b64 v[32:33], 11, v[32:33]
	v_lshl_add_u64 v[32:33], s[50:51], 0, v[32:33]
	v_mov_b32_e32 v35, v34
	s_and_saveexec_b64 s[26:27], vcc
	s_cbranch_execz .LBB0_432
	v_mov_b32_e32 v36, v34
	v_mov_b32_e32 v37, v34
	v_pk_mul_f32 v[30:31], v[30:31], v[36:37]
	v_pk_mul_f32 v[28:29], v[28:29], v[34:35]
	v_pk_mul_f32 v[36:37], v[26:27], v[36:37]
	v_pk_mul_f32 v[26:27], v[24:25], v[34:35]
	v_cvt_pk_bf16_f32 v24, v28, v29
	v_cvt_pk_bf16_f32 v25, v30, v31
	v_cvt_pk_bf16_f32 v26, v26, v27
	v_cvt_pk_bf16_f32 v27, v36, v37
	v_lshl_add_u64 v[28:29], v[140:141], 1, v[32:33]
	global_store_dwordx4 v[28:29], v[24:27], off

; DI unsigned pk2(float lo, float hi) { const f32x2 v = {lo, hi}; const hwbf16x2 b = __builtin_convertvector(v, hwbf16x2); return __builtin_bit_cast(unsigned, b); }
; DI float frsq(float x) { return __builtin_amdgcn_rsqf(x); }
;     DI void operator()(const f32x4 (&acc)[2][2][4][2], const Unit& u, int wr, int wc, int fr, int fq) const {
;     ...
;                 const int row = row0 + ai * HALF + m * 16;
;                 float rs = 1.f, rowacc = 0.f;
;                 if (mode == EPI_STORE || mode == EPI_Q) { if (rscale) rs = rscale[row]; }
;                 if (mode == EPI_SWIGLU) rs = frsq(rowsq[row] * (1.0f / DM) + 1e-6f);
; #pragma unroll
;                 for (int bj = 0; bj < 2; ++bj) {
;                     const int col = col0 + bj * HALF;
;                     f32x4 v0 = acc[ai][bj][m][0], v1 = acc[ai][bj][m][1];
;                     if (mode == EPI_STORE) {
;                         if (col < ncols) { v0 = v0 * rs; v1 = v1 * rs; u32x4 w; w.x = pk2(v0[0], v0[1]); w.y = pk2(v0[2], v0[3]); w.z = pk2(v1[0], v1[1]); w.w = pk2(v1[2], v1[3]);
;                             *(u32x4*)(O + (size_t)row * ldc + col) = w; }
.LBB0_434:
	s_or_b64 exec, exec, s[26:27]
	v_mov_b32_e32 v18, v243
	v_add_u32_e32 v16, 0xb0, v142
	v_ashrrev_i32_e32 v17, 31, v16
	v_lshlrev_b64 v[16:17], 11, v[16:17]
	v_lshl_add_u64 v[16:17], s[50:51], 0, v[16:17]
	v_mov_b32_e32 v19, v18
	s_and_saveexec_b64 s[26:27], vcc
	s_cbranch_execz .LBB0_437
	v_mov_b32_e32 v20, v18
	v_mov_b32_e32 v21, v18
	v_pk_mul_f32 v[14:15], v[14:15], v[20:21]
	v_pk_mul_f32 v[12:13], v[12:13], v[18:19]
	v_pk_mul_f32 v[20:21], v[10:11], v[20:21]
	v_pk_mul_f32 v[10:11], v[8:9], v[18:19]
	v_cvt_pk_bf16_f32 v8, v12, v13
	v_cvt_pk_bf16_f32 v9, v14, v15
	v_cvt_pk_bf16_f32 v10, v10, v11
	v_cvt_pk_bf16_f32 v11, v20, v21
	v_lshl_add_u64 v[12:13], v[140:141], 1, v[16:17]
	global_store_dwordx4 v[12:13], v[8:11], off
	s_or_b64 exec, exec, s[26:27]
	s_and_saveexec_b64 s[26:27], s[6:7]
	s_cbranch_execnz .LBB0_438
